# early L2 write-back (buffer_wbl2 by wave 0) on arrival at each grid barrier, so the XCD leader's release fence finds little dirty data
# baseline (speedup 1.0000x reference)
; __device__ __forceinline__ void xcd_barrier(unsigned* bar, unsigned x, volatile LAS unsigned* st, bool leader_thread) {
;     asm volatile("s_waitcnt vmcnt(0)" ::: "memory");
;     __syncthreads();
;     if (leader_thread) {
;         __builtin_amdgcn_s_waitcnt(0);
;         unsigned nloc = st[0], nx = st[1];
;         if (nloc == 0u) { xcd_barrier_complete(bar, x, nloc, nx); st[0] = nloc; st[1] = nx; }
.LBB0_99:
	s_mov_b64 s[48:49], s[16:17]
	v_mbcnt_lo_u32_b32 v0, -1, 0
	v_mbcnt_hi_u32_b32 v0, -1, v0
	s_cmp_lg_u32 s3, 0
	s_cbranch_scc1 .Lwb_skip1
	buffer_wbl2 sc1
.Lwb_skip1:
	s_waitcnt vmcnt(0)
	s_waitcnt vmcnt(0)
	v_cmp_eq_u32_e32 vcc, 0, v0
	s_and_b64 s[22:23], vcc, s[94:95]
	s_barrier
	s_and_saveexec_b64 s[26:27], s[22:23]
	s_cbranch_execz .LBB0_151
	v_mov_b32_e32 v0, s9
	s_waitcnt vmcnt(0) expcnt(0) lgkmcnt(0)
	ds_read_b32 v2, v0
	v_mov_b32_e32 v0, s34
	ds_read_b32 v0, v0
	s_waitcnt lgkmcnt(1)
	v_cmp_ne_u32_e32 vcc, 0, v2
	s_cbranch_vccnz .LBB0_115
	s_add_u32 s28, s48, 0x1000
	s_addc_u32 s29, s49, 0
	s_add_u32 s36, s48, 0x1100
	s_addc_u32 s37, s49, 0
	s_add_u32 s38, s48, 0x1200
	s_addc_u32 s39, s49, 0
	s_add_u32 s40, s48, 0x1300
	s_addc_u32 s41, s49, 0
	s_mov_b32 s2, 1
	s_branch .LBB0_103

; __device__ __forceinline__ void xcd_barrier(unsigned* bar, unsigned x, volatile LAS unsigned* st, bool leader_thread) {
;     asm volatile("s_waitcnt vmcnt(0)" ::: "memory");
;     __syncthreads();
;     if (leader_thread) {
;         __builtin_amdgcn_s_waitcnt(0);
;         unsigned nloc = st[0], nx = st[1];
;         if (nloc == 0u) { xcd_barrier_complete(bar, x, nloc, nx); st[0] = nloc; st[1] = nx; }
.Lwb_skip2:
	s_waitcnt vmcnt(0)
	s_waitcnt vmcnt(0)
	v_cmp_eq_u32_e32 vcc, 0, v0
	s_and_b64 s[22:23], vcc, s[94:95]
	s_barrier
	s_and_saveexec_b64 s[24:25], s[22:23]
	s_cbranch_execz .LBB0_243
	v_mov_b32_e32 v0, s9
	s_waitcnt vmcnt(0) expcnt(0) lgkmcnt(0)
	ds_read_b32 v2, v0
	v_mov_b32_e32 v0, s34
	ds_read_b32 v0, v0
	s_waitcnt lgkmcnt(1)
	v_cmp_ne_u32_e32 vcc, 0, v2
	s_cbranch_vccnz .LBB0_207
	s_add_u32 s28, s48, 0x1000
	s_addc_u32 s29, s49, 0
	s_add_u32 s36, s48, 0x1100
	s_addc_u32 s37, s49, 0
	s_add_u32 s38, s48, 0x1200
	s_addc_u32 s39, s49, 0
	s_add_u32 s40, s48, 0x1300
	s_addc_u32 s41, s49, 0
	s_mov_b32 s2, 1
	s_branch .LBB0_195

; __device__ __forceinline__ void xcd_barrier(unsigned* bar, unsigned x, volatile LAS unsigned* st, bool leader_thread) {
;     asm volatile("s_waitcnt vmcnt(0)" ::: "memory");
;     __syncthreads();
;     if (leader_thread) {
;         __builtin_amdgcn_s_waitcnt(0);
;         unsigned nloc = st[0], nx = st[1];
;         if (nloc == 0u) { xcd_barrier_complete(bar, x, nloc, nx); st[0] = nloc; st[1] = nx; }
.LBB0_250:
	s_or_b64 exec, exec, s[24:25]
	v_mbcnt_lo_u32_b32 v0, -1, 0
	v_mbcnt_hi_u32_b32 v0, -1, v0
	s_cmp_lg_u32 s3, 0
	s_cbranch_scc1 .Lwb_skip3
	buffer_wbl2 sc1
.Lwb_skip3:
	s_waitcnt vmcnt(0)
	s_nop 0
	v_cmp_eq_u32_e32 vcc, 0, v0
	s_and_b64 s[22:23], vcc, s[94:95]
	s_barrier
	s_and_saveexec_b64 s[24:25], s[22:23]
	s_cbranch_execz .LBB0_302
	v_mov_b32_e32 v0, s9
	s_waitcnt vmcnt(0) expcnt(0) lgkmcnt(0)
	ds_read_b32 v2, v0
	v_mov_b32_e32 v0, s34
	ds_read_b32 v0, v0
	s_waitcnt lgkmcnt(1)
	v_cmp_ne_u32_e32 vcc, 0, v2
	s_cbranch_vccnz .LBB0_266
	s_add_u32 s28, s48, 0x1000
	s_addc_u32 s29, s49, 0
	s_add_u32 s38, s48, 0x1100
	s_addc_u32 s39, s49, 0
	s_add_u32 s40, s48, 0x1200
	s_addc_u32 s41, s49, 0
	s_add_u32 s50, s48, 0x1300
	s_addc_u32 s51, s49, 0
	s_mov_b32 s2, 1
	s_branch .LBB0_254

; __device__ __forceinline__ void xcd_barrier(unsigned* bar, unsigned x, volatile LAS unsigned* st, bool leader_thread) {
;     asm volatile("s_waitcnt vmcnt(0)" ::: "memory");
;     __syncthreads();
;     if (leader_thread) {
;         __builtin_amdgcn_s_waitcnt(0);
;         unsigned nloc = st[0], nx = st[1];
;         if (nloc == 0u) { xcd_barrier_complete(bar, x, nloc, nx); st[0] = nloc; st[1] = nx; }
.LBB0_328:
	v_mbcnt_lo_u32_b32 v0, -1, 0
	v_mbcnt_hi_u32_b32 v0, -1, v0
	s_cmp_lg_u32 s3, 0
	s_cbranch_scc1 .Lwb_skip4
	buffer_wbl2 sc1
.Lwb_skip4:
	s_waitcnt vmcnt(0)
	s_waitcnt lgkmcnt(0)
	v_cmp_eq_u32_e32 vcc, 0, v0
	s_and_b64 s[22:23], vcc, s[94:95]
	s_barrier
	s_and_saveexec_b64 s[26:27], s[22:23]
	s_cbranch_execz .LBB0_380
	v_mov_b32_e32 v0, s9
	s_waitcnt vmcnt(0) expcnt(0) lgkmcnt(0)
	ds_read_b32 v2, v0
	v_mov_b32_e32 v0, s34
	ds_read_b32 v0, v0
	s_waitcnt lgkmcnt(1)
	v_cmp_ne_u32_e32 vcc, 0, v2
	s_cbranch_vccnz .LBB0_344
	s_add_u32 s28, s48, 0x1000
	s_addc_u32 s29, s49, 0
	s_add_u32 s36, s48, 0x1100
	s_addc_u32 s37, s49, 0
	s_add_u32 s40, s48, 0x1200
	s_addc_u32 s41, s49, 0
	s_add_u32 s50, s48, 0x1300
	s_addc_u32 s51, s49, 0
	s_mov_b32 s2, 1
	s_branch .LBB0_332

; __device__ __forceinline__ void scan_phase(LAS unsigned char* lds, const bf16_t* om, const bf16_t* bx, const bf16_t* gate, bf16_t* y, int tid, int G) {
;     ...
;     __syncthreads();
; __device__ __forceinline__ void xcd_barrier(unsigned* bar, unsigned x, volatile LAS unsigned* st, bool leader_thread) {
;     asm volatile("s_waitcnt vmcnt(0)" ::: "memory");
;     __syncthreads();
;     if (leader_thread) {
;         __builtin_amdgcn_s_waitcnt(0);
;         unsigned nloc = st[0], nx = st[1];
;         if (nloc == 0u) { xcd_barrier_complete(bar, x, nloc, nx); st[0] = nloc; st[1] = nx; }
.LBB0_391:
	s_barrier
	v_mbcnt_lo_u32_b32 v0, -1, 0
	v_mbcnt_hi_u32_b32 v0, -1, v0
	s_cmp_lg_u32 s3, 0
	s_cbranch_scc1 .Lwb_skip5
	buffer_wbl2 sc1
.Lwb_skip5:
	s_waitcnt vmcnt(0)
	s_nop 0
	v_cmp_eq_u32_e32 vcc, 0, v0
	s_and_b64 s[22:23], vcc, s[94:95]
	s_barrier
	s_and_saveexec_b64 s[26:27], s[22:23]
	s_cbranch_execz .LBB0_443
	v_mov_b32_e32 v0, s9
	s_waitcnt vmcnt(0) expcnt(0) lgkmcnt(0)
	ds_read_b32 v2, v0
	v_mov_b32_e32 v0, s34
	ds_read_b32 v0, v0
	s_waitcnt lgkmcnt(1)
	v_cmp_ne_u32_e32 vcc, 0, v2
	s_cbranch_vccnz .LBB0_407
	s_add_u32 s28, s48, 0x1000
	s_addc_u32 s29, s49, 0
	s_add_u32 s36, s48, 0x1100
	s_addc_u32 s37, s49, 0
	s_add_u32 s38, s48, 0x1200
	s_addc_u32 s39, s49, 0
	s_add_u32 s40, s48, 0x1300
	s_addc_u32 s41, s49, 0
	s_mov_b32 s2, 1
	s_branch .LBB0_395

; __device__ __forceinline__ void xcd_barrier(unsigned* bar, unsigned x, volatile LAS unsigned* st, bool leader_thread) {
;     asm volatile("s_waitcnt vmcnt(0)" ::: "memory");
;     __syncthreads();
;     if (leader_thread) {
;         __builtin_amdgcn_s_waitcnt(0);
;         unsigned nloc = st[0], nx = st[1];
;         if (nloc == 0u) { xcd_barrier_complete(bar, x, nloc, nx); st[0] = nloc; st[1] = nx; }
.Lwb_skip6:
	s_waitcnt vmcnt(0)
	s_waitcnt vmcnt(0) lgkmcnt(0)
	v_cmp_eq_u32_e32 vcc, 0, v0
	s_and_b64 s[22:23], vcc, s[94:95]
	s_barrier
	s_and_saveexec_b64 s[24:25], s[22:23]
	s_cbranch_execz .LBB0_525
	v_mov_b32_e32 v0, s9
	s_waitcnt vmcnt(0) expcnt(0) lgkmcnt(0)
	ds_read_b32 v2, v0
	v_mov_b32_e32 v0, s34
	ds_read_b32 v0, v0
	s_waitcnt lgkmcnt(1)
	v_cmp_ne_u32_e32 vcc, 0, v2
	s_cbranch_vccnz .LBB0_489
	s_add_u32 s28, s16, 0x1000
	s_addc_u32 s29, s17, 0
	s_add_u32 s36, s16, 0x1100
	s_addc_u32 s37, s17, 0
	s_add_u32 s38, s16, 0x1200
	s_addc_u32 s39, s17, 0
	s_add_u32 s40, s16, 0x1300
	s_addc_u32 s41, s17, 0
	s_mov_b32 s2, 1
	s_branch .LBB0_477

; __device__ __forceinline__ void conv_phase(LAS unsigned char* lds, const bf16_t* glu, bf16_t* cat, const float* cw, const float* cb, const float* lg, const float* lb, int tid, int G) {
;     ...
;     __syncthreads();
; __device__ __forceinline__ void xcd_barrier(unsigned* bar, unsigned x, volatile LAS unsigned* st, bool leader_thread) {
;     asm volatile("s_waitcnt vmcnt(0)" ::: "memory");
;     __syncthreads();
;     if (leader_thread) {
;         __builtin_amdgcn_s_waitcnt(0);
;         unsigned nloc = st[0], nx = st[1];
;         if (nloc == 0u) { xcd_barrier_complete(bar, x, nloc, nx); st[0] = nloc; st[1] = nx; }
.LBB0_607:
	s_mov_b64 s[48:49], s[16:17]
	s_waitcnt vmcnt(63) expcnt(7) lgkmcnt(15)
	s_barrier
	s_waitcnt vmcnt(3)
	v_mbcnt_lo_u32_b32 v0, -1, 0
	v_mbcnt_hi_u32_b32 v0, -1, v0
	s_cmp_lg_u32 s3, 0
	s_cbranch_scc1 .Lwb_skip7
	buffer_wbl2 sc1
.Lwb_skip7:
	s_waitcnt vmcnt(0)
	s_nop 0
	v_cmp_eq_u32_e32 vcc, 0, v0
	s_and_b64 s[22:23], vcc, s[94:95]
	s_barrier
	s_and_saveexec_b64 s[16:17], s[22:23]
	s_cbranch_execz .LBB0_659
	v_mov_b32_e32 v0, s9
	s_waitcnt vmcnt(0) expcnt(0) lgkmcnt(0)
	ds_read_b32 v2, v0
	v_mov_b32_e32 v0, s34
	ds_read_b32 v0, v0
	s_waitcnt lgkmcnt(1)
	v_cmp_ne_u32_e32 vcc, 0, v2
	s_cbranch_vccnz .LBB0_623
	s_add_u32 s26, s48, 0x1000
	s_addc_u32 s27, s49, 0
	s_add_u32 s28, s48, 0x1100
	s_addc_u32 s29, s49, 0
	s_add_u32 s36, s48, 0x1200
	s_addc_u32 s37, s49, 0
	s_add_u32 s38, s48, 0x1300
	s_addc_u32 s39, s49, 0
	s_mov_b32 s2, 1
	s_branch .LBB0_611

; #define GRID_BAR() do { asm volatile("" : "+s"(barw)); xcd_barrier((unsigned*)barw, bxcc, bst, lane_id_asm() == 0 && wave_s == 0); } while (0)
; __device__ __forceinline__ void xcd_barrier(unsigned* bar, unsigned x, volatile LAS unsigned* st, bool leader_thread) {
;     asm volatile("s_waitcnt vmcnt(0)" ::: "memory");
;     __syncthreads();
;     if (leader_thread) {
;         __builtin_amdgcn_s_waitcnt(0);
;         unsigned nloc = st[0], nx = st[1];
;         if (nloc == 0u) { xcd_barrier_complete(bar, x, nloc, nx); st[0] = nloc; st[1] = nx; }
; __global__ void __launch_bounds__(512, 2) hybrid_fwd(Args A) {
;     ...
;             GRID_BAR();
.LBB0_709:
	s_mov_b64 s[16:17], s[48:49]
	v_mbcnt_lo_u32_b32 v0, -1, 0
	v_mbcnt_hi_u32_b32 v0, -1, v0
	s_cmp_lg_u32 s3, 0
	s_cbranch_scc1 .Lwb_skip8
	buffer_wbl2 sc1
.Lwb_skip8:
	s_waitcnt vmcnt(0)
	s_nop 0
	v_cmp_eq_u32_e32 vcc, 0, v0
	s_and_b64 s[0:1], vcc, s[94:95]
	s_barrier
	s_and_saveexec_b64 s[24:25], s[0:1]
	s_cbranch_execz .LBB0_73
	v_mov_b32_e32 v0, s9
	s_waitcnt vmcnt(0) expcnt(0) lgkmcnt(0)
	ds_read_b32 v2, v0
	v_mov_b32_e32 v0, s34
	ds_read_b32 v0, v0
	s_waitcnt lgkmcnt(1)
	v_cmp_ne_u32_e32 vcc, 0, v2
	s_cbranch_vccnz .LBB0_725
	s_add_u32 s26, s16, 0x1000
	s_addc_u32 s27, s17, 0
	s_add_u32 s28, s16, 0x1100
	s_addc_u32 s29, s17, 0
	s_add_u32 s36, s16, 0x1200
	s_addc_u32 s37, s17, 0
	s_add_u32 s38, s16, 0x1300
	s_addc_u32 s39, s17, 0
	s_mov_b32 s0, 1
	s_branch .LBB0_713
